# stack + PLE-gate epilogue: first row group's h1/ple tiles loaded before the K-loop, first vmcnt(0) replaced by vmcnt(7) before the second group
# speedup vs baseline: 1.0080x; 1.0080x over previous
; #define GATE_LOAD(r, b) do { const int row_ = row0 + ((r) >> 2) * 128 + ((r) & 3) * 16; _Pragma("unroll") for (int bj = 0; bj < 2; ++bj) { const size_t off_ = (size_t)row_ * DM + col0 + bj * 128; \
;             hA[b][bj] = *(const u32x4*)(H1 + off_); pA[b][bj] = *(const u32x4*)(PLE + off_); } } while (0)
; template <class Epi, class Order = StaticOrder, bool HALFN = false>
; __device__ __forceinline__ void gemm_phase(LAS unsigned char* lds, const Gemm g, const Epi& E) {
;     ...
;         else {
; #pragma unroll
;         for (int a = 0; a < 2; ++a)
; #pragma unroll
;             for (int b = 0; b < 2; ++b)
; #pragma unroll
;                 for (int m = 0; m < 4; ++m)
; #pragma unroll
;                     for (int n = 0; n < 2; ++n) acc[a][b][m][n] = (f32x4){0.f, 0.f, 0.f, 0.f};
;         }
;         cur = nxt; cA = nA; cB = nB; ++ui;
;     __device__ __forceinline__ void operator()(f32x4 (&acc)[2][2][4][2], const Unit& u, int wr, int wc, int fr, int fq) const {
;     ...
;         GATE_LOAD(0, 0);
.LBB0_798:
	s_mov_b32 s50, s23
	s_ashr_i32 s51, s23, 31
	s_lshl_b64 s[4:5], s[50:51], 20
	s_add_u32 s74, s66, s4
	s_addc_u32 s75, s67, s5
	s_and_b64 s[4:5], s[54:55], exec
	s_mov_b32 s52, s7
	s_cselect_b32 s23, s75, s43
	s_cselect_b32 s24, s74, s42
	s_ashr_i32 s53, s7, 31
	s_lshl_b64 s[4:5], s[52:53], 20
	s_add_u32 s82, s8, s4
	s_addc_u32 s83, s9, s5
	s_and_b64 s[4:5], s[54:55], exec
	s_cselect_b32 s25, s83, s81
	s_cselect_b32 s26, s82, s80
	s_add_u32 s62, s42, 0x80080
	s_addc_u32 s63, s43, 0
	s_add_u32 s27, s80, 0x100
	v_mov_b32_e32 v2, 0
	s_addc_u32 s28, s81, 0
	s_mov_b32 s29, -2
	s_waitcnt lgkmcnt(0)
	v_mov_b32_e32 v3, v2
	v_mov_b32_e32 v4, v2
	v_mov_b32_e32 v5, v2
	v_mov_b32_e32 v6, v2
	v_mov_b32_e32 v7, v2
	v_mov_b32_e32 v8, v2
	v_mov_b32_e32 v9, v2
	v_mov_b32_e32 v18, v2
	v_mov_b32_e32 v19, v2
	v_mov_b32_e32 v20, v2
	v_mov_b32_e32 v21, v2
	v_mov_b32_e32 v22, v2
	v_mov_b32_e32 v23, v2
	v_mov_b32_e32 v24, v2
	v_mov_b32_e32 v25, v2
	v_mov_b32_e32 v34, v2
	v_mov_b32_e32 v35, v2
	v_mov_b32_e32 v36, v2
	v_mov_b32_e32 v37, v2
	v_mov_b32_e32 v38, v2
	v_mov_b32_e32 v39, v2
	v_mov_b32_e32 v40, v2
	v_mov_b32_e32 v41, v2
	v_mov_b32_e32 v50, v2
	v_mov_b32_e32 v51, v2
	v_mov_b32_e32 v52, v2
	v_mov_b32_e32 v53, v2
	v_mov_b32_e32 v54, v2
	v_mov_b32_e32 v55, v2
	v_mov_b32_e32 v56, v2
	v_mov_b32_e32 v57, v2
	v_mov_b32_e32 v10, v2
	v_mov_b32_e32 v11, v2
	v_mov_b32_e32 v12, v2
	v_mov_b32_e32 v13, v2
	v_mov_b32_e32 v14, v2
	v_mov_b32_e32 v15, v2
	v_mov_b32_e32 v16, v2
	v_mov_b32_e32 v17, v2
	v_mov_b32_e32 v26, v2
	v_mov_b32_e32 v27, v2
	v_mov_b32_e32 v28, v2
	v_mov_b32_e32 v29, v2
	v_mov_b32_e32 v30, v2
	v_mov_b32_e32 v31, v2
	v_mov_b32_e32 v32, v2
	v_mov_b32_e32 v33, v2
	v_mov_b32_e32 v42, v2
	v_mov_b32_e32 v43, v2
	v_mov_b32_e32 v44, v2
	v_mov_b32_e32 v45, v2
	v_mov_b32_e32 v46, v2
	v_mov_b32_e32 v47, v2
	v_mov_b32_e32 v48, v2
	v_mov_b32_e32 v49, v2
	v_mov_b32_e32 v58, v2
	v_mov_b32_e32 v59, v2
	v_mov_b32_e32 v60, v2
	v_mov_b32_e32 v61, v2
	v_mov_b32_e32 v62, v2
	v_mov_b32_e32 v63, v2
	v_mov_b32_e32 v64, v2
	v_mov_b32_e32 v65, v2
	v_mov_b32_e32 v66, v2
	v_mov_b32_e32 v67, v2
	v_mov_b32_e32 v68, v2
	v_mov_b32_e32 v69, v2
	v_mov_b32_e32 v70, v2
	v_mov_b32_e32 v71, v2
	v_mov_b32_e32 v72, v2
	v_mov_b32_e32 v73, v2
	v_mov_b32_e32 v82, v2
	v_mov_b32_e32 v83, v2
	v_mov_b32_e32 v84, v2
	v_mov_b32_e32 v85, v2
	v_mov_b32_e32 v86, v2
	v_mov_b32_e32 v87, v2
	v_mov_b32_e32 v88, v2
	v_mov_b32_e32 v89, v2
	v_mov_b32_e32 v98, v2
	v_mov_b32_e32 v99, v2
	v_mov_b32_e32 v100, v2
	v_mov_b32_e32 v101, v2
	v_mov_b32_e32 v102, v2
	v_mov_b32_e32 v103, v2
	v_mov_b32_e32 v104, v2
	v_mov_b32_e32 v105, v2
	v_mov_b32_e32 v114, v2
	v_mov_b32_e32 v115, v2
	v_mov_b32_e32 v116, v2
	v_mov_b32_e32 v117, v2
	v_mov_b32_e32 v118, v2
	v_mov_b32_e32 v119, v2
	v_mov_b32_e32 v120, v2
	v_mov_b32_e32 v121, v2
	v_mov_b32_e32 v74, v2
	v_mov_b32_e32 v75, v2
	v_mov_b32_e32 v76, v2
	v_mov_b32_e32 v77, v2
	v_mov_b32_e32 v78, v2
	v_mov_b32_e32 v79, v2
	v_mov_b32_e32 v80, v2
	v_mov_b32_e32 v81, v2
	v_mov_b32_e32 v90, v2
	v_mov_b32_e32 v91, v2
	v_mov_b32_e32 v92, v2
	v_mov_b32_e32 v93, v2
	v_mov_b32_e32 v94, v2
	v_mov_b32_e32 v95, v2
	v_mov_b32_e32 v96, v2
	v_mov_b32_e32 v97, v2
	v_mov_b32_e32 v106, v2
	v_mov_b32_e32 v107, v2
	v_mov_b32_e32 v108, v2
	v_mov_b32_e32 v109, v2
	v_mov_b32_e32 v110, v2
	v_mov_b32_e32 v111, v2
	v_mov_b32_e32 v112, v2
	v_mov_b32_e32 v113, v2
	v_mov_b32_e32 v126, v2
	v_mov_b32_e32 v127, v2
	v_mov_b32_e32 v128, v2
	v_mov_b32_e32 v129, v2
	v_mov_b32_e32 v134, v2
	v_mov_b32_e32 v135, v2
	v_mov_b32_e32 v136, v2
	v_mov_b32_e32 v137, v2
	s_lshl_b32 s98, s94, 8
	s_add_i32 s98, s98, s18
	v_add_u32_e32 v246, s98, v1
	s_lshl_b32 s98, s92, 8
	s_or_b32 s98, s98, s19
	v_lshl_add_u32 v248, v208, 3, s98
	v_ashrrev_i32_e32 v247, 31, v246
	v_ashrrev_i32_e32 v249, 31, v248
	v_lshlrev_b64 v[246:247], 11, v[246:247]
	v_lshl_add_u64 v[246:247], v[246:247], 0, v[248:249]
	v_lshlrev_b64 v[246:247], 1, v[246:247]
	v_lshl_add_u64 v[248:249], s[66:67], 0, v[246:247]
	global_load_dwordx4 v[192:195], v[248:249], off
	global_load_dwordx4 v[200:203], v[248:249], off offset:256
	s_mul_i32 s98, s92, 0x1e00
	s_mul_i32 s99, s19, 62
	s_add_i32 s98, s98, s99
	s_movk_i32 s99, 0xf010
	v_lshlrev_b32_e32 v248, 8, v208
	v_lshlrev_b32_e32 v249, 4, v208
	v_sub_u32_e32 v248, v248, v249
	v_add_u32_e32 v248, s98, v248
	v_mad_i32_i24 v248, v1, s99, v248
	v_ashrrev_i32_e32 v249, 31, v248
	v_lshl_add_u64 v[246:247], s[44:45], 0, v[246:247]
	v_lshl_add_u64 v[246:247], v[246:247], 0, v[248:249]
	global_load_dwordx4 v[196:199], v[246:247], off
	global_load_dwordx4 v[204:207], v[246:247], off offset:1024

; __device__ __forceinline__ float sigmoid_f(float x) { return __builtin_amdgcn_rcpf(1.0f + __builtin_amdgcn_exp2f(-1.4426950409f * x)); }
; __device__ __forceinline__ u32x4 pack8(f32x4 a, f32x4 b) { u32x4 w; w.x = cvt_pk_bf16(a[0], a[1]); w.y = cvt_pk_bf16(a[2], a[3]); w.z = cvt_pk_bf16(b[0], b[1]); w.w = cvt_pk_bf16(b[2], b[3]); return w; }
; __device__ __forceinline__ void unpack8(u32x4 g, f32x4& a, f32x4& b) { a = (f32x4){bf_lo(g.x), bf_hi(g.x), bf_lo(g.y), bf_hi(g.y)}; b = (f32x4){bf_lo(g.z), bf_hi(g.z), bf_lo(g.w), bf_hi(g.w)}; }
; #define GATE_LOAD(r, b) do { const int row_ = row0 + ((r) >> 2) * 128 + ((r) & 3) * 16; _Pragma("unroll") for (int bj = 0; bj < 2; ++bj) { const size_t off_ = (size_t)row_ * DM + col0 + bj * 128; \
;             hA[b][bj] = *(const u32x4*)(H1 + off_); pA[b][bj] = *(const u32x4*)(PLE + off_); } } while (0)
;     __device__ __forceinline__ void operator()(f32x4 (&acc)[2][2][4][2], const Unit& u, int wr, int wc, int fr, int fq) const {
;     ...
;         GATE_LOAD(0, 0);
; #pragma unroll
;         for (int r = 0; r < 8; ++r) {
;             const int ai = r >> 2, m = r & 3, b = r & 1;
;             if (r + 1 < 8) GATE_LOAD(r + 1, (r + 1) & 1);
;             const int row = row0 + ai * 128 + m * 16;
;             float ss = 0.f;
; #pragma unroll
;             for (int bj = 0; bj < 2; ++bj) {
;                 const size_t off = (size_t)row * DM + col0 + bj * 128;
;                 f32x4 p0, p1, o0, o1; unpack8(pA[b][bj], p0, p1); unpack8(hA[b][bj], o0, o1);
; #pragma unroll
;                 for (int j = 0; j < 4; ++j) { o0[j] += sigmoid_f(acc[ai][bj][m][0][j]) * p0[j]; o1[j] += sigmoid_f(acc[ai][bj][m][1][j]) * p1[j]; }
;                 *(u32x4*)(HB + off) = pack8(o0, o1);
; #pragma unroll
;                 for (int j = 0; j < 4; ++j) ss += o0[j] * o0[j] + o1[j] * o1[j];
;             }
;             ss += __shfl_xor(ss, 16); ss += __shfl_xor(ss, 32);
;             if (fq == 0) atomicAdd(ssq + row, ss);
.LBB0_802:
	s_lshl_b32 s4, s94, 8
	v_mov_b32_e32 v122, v1
	v_mov_b32_e32 v130, v208
	s_add_i32 s4, s4, s18
	s_mul_i32 s98, s92, 0x1e00
	s_mul_i32 s99, s19, 62
	s_add_i32 s98, s98, s99
	s_movk_i32 s99, 0xf010
	v_lshlrev_b32_e32 v246, 8, v208
	v_lshlrev_b32_e32 v247, 4, v208
	v_sub_u32_e32 v246, v246, v247
	v_add_u32_e32 v246, s98, v246
	v_mad_i32_i24 v246, v1, s99, v246
	v_ashrrev_i32_e32 v247, 31, v246
	v_mul_f32_e32 v134, 0xbfb8aa3b, v134
	v_add_u32_e32 v182, s4, v122
	s_lshl_b32 s4, s92, 8
	s_or_b32 s4, s4, s19
	v_lshl_add_u32 v180, v130, 3, s4
	v_ashrrev_i32_e32 v183, 31, v182
	v_lshlrev_b64 v[122:123], 11, v[182:183]
	v_ashrrev_i32_e32 v181, 31, v180
	v_lshl_add_u64 v[122:123], v[122:123], 0, v[180:181]
	v_lshlrev_b64 v[122:123], 1, v[122:123]
	v_lshl_add_u64 v[124:125], s[66:67], 0, v[122:123]
	v_lshl_add_u64 v[122:123], s[44:45], 0, v[122:123]
	v_lshl_add_u64 v[122:123], v[122:123], 0, v[246:247]
	v_and_b32_e32 v123, 64, v191
	v_xor_b32_e32 v122, 16, v191
	v_add_u32_e32 v123, 64, v123
	v_cmp_lt_i32_e32 vcc, v122, v123
	v_add_u32_e32 v184, 16, v182
	v_ashrrev_i32_e32 v185, 31, v184
	v_cndmask_b32_e32 v122, v191, v122, vcc
	v_lshlrev_b32_e32 v211, 2, v122
	v_xor_b32_e32 v122, 32, v191
	v_cmp_lt_i32_e32 vcc, v122, v123
	v_mul_f32_e32 v135, 0xbfb8aa3b, v135
	v_mul_f32_e32 v136, 0xbfb8aa3b, v136
	v_cndmask_b32_e32 v122, v191, v122, vcc
	v_lshlrev_b32_e32 v212, 2, v122
	v_lshlrev_b64 v[122:123], 11, v[184:185]
	v_lshl_add_u64 v[122:123], v[122:123], 0, v[180:181]
	v_lshlrev_b64 v[122:123], 1, v[122:123]
	v_cmp_eq_u32_e32 vcc, 0, v130
	v_lshl_add_u64 v[124:125], s[66:67], 0, v[122:123]
	v_lshl_add_u64 v[130:131], s[44:45], 0, v[122:123]
	v_lshl_add_u64 v[130:131], v[130:131], 0, v[246:247]
	global_load_dwordx4 v[138:141], v[124:125], off
	global_load_dwordx4 v[142:145], v[130:131], off
	s_nop 0
	global_load_dwordx4 v[122:125], v[124:125], off offset:256
	s_nop 0
	global_load_dwordx4 v[130:133], v[130:131], off offset:1024
	v_mul_f32_e32 v137, 0xbfb8aa3b, v137
	v_exp_f32_e32 v134, v134
	v_mul_f32_e32 v126, 0xbfb8aa3b, v126
	v_exp_f32_e32 v135, v135
	v_mul_f32_e32 v127, 0xbfb8aa3b, v127
	v_exp_f32_e32 v136, v136
	v_mul_f32_e32 v128, 0xbfb8aa3b, v128
	v_exp_f32_e32 v137, v137
	v_mul_f32_e32 v129, 0xbfb8aa3b, v129
	v_exp_f32_e32 v126, v126
	v_exp_f32_e32 v127, v127
	v_exp_f32_e32 v128, v128
	v_exp_f32_e32 v129, v129
	v_mul_f32_e32 v118, 0xbfb8aa3b, v118
	v_mul_f32_e32 v119, 0xbfb8aa3b, v119
	v_add_f32_e32 v134, 1.0, v134
	v_add_f32_e32 v135, 1.0, v135
	v_add_f32_e32 v136, 1.0, v136
	v_add_f32_e32 v137, 1.0, v137
	v_exp_f32_e32 v118, v118
	v_mul_f32_e32 v114, 0xbfb8aa3b, v114
	v_exp_f32_e32 v119, v119
	v_mul_f32_e32 v115, 0xbfb8aa3b, v115
	v_rcp_f32_e32 v134, v134
	v_add_f32_e32 v126, 1.0, v126
	v_rcp_f32_e32 v135, v135
	v_add_f32_e32 v127, 1.0, v127
	v_rcp_f32_e32 v136, v136
	v_add_f32_e32 v128, 1.0, v128
	v_rcp_f32_e32 v137, v137
	v_add_f32_e32 v129, 1.0, v129
	v_exp_f32_e32 v114, v114
	v_exp_f32_e32 v115, v115
	v_rcp_f32_e32 v126, v126
	v_rcp_f32_e32 v127, v127
	v_rcp_f32_e32 v128, v128
	v_rcp_f32_e32 v129, v129
	v_add_f32_e32 v118, 1.0, v118
	v_add_f32_e32 v119, 1.0, v119
	v_rcp_f32_e32 v118, v118
	v_add_f32_e32 v114, 1.0, v114
	v_rcp_f32_e32 v119, v119
	v_add_f32_e32 v115, 1.0, v115
	v_rcp_f32_e32 v114, v114
	v_rcp_f32_e32 v115, v115
	v_lshlrev_b64 v[186:187], 12, v[182:183]
	v_lshlrev_b32_e32 v214, 16, v196
	v_and_b32_e32 v215, 0xffff0000, v196
	v_lshlrev_b32_e32 v216, 16, v192
	v_and_b32_e32 v217, 0xffff0000, v192
	v_lshlrev_b32_e32 v158, 16, v197
	v_and_b32_e32 v159, 0xffff0000, v197
	v_lshlrev_b32_e32 v154, 16, v193
	v_and_b32_e32 v155, 0xffff0000, v193
	v_pk_fma_f32 v[134:135], v[134:135], v[214:215], v[216:217]
	v_lshlrev_b32_e32 v214, 16, v198
	v_and_b32_e32 v215, 0xffff0000, v198
	v_lshlrev_b32_e32 v216, 16, v194
	v_and_b32_e32 v217, 0xffff0000, v194
	v_pk_fma_f32 v[136:137], v[136:137], v[158:159], v[154:155]
	v_lshlrev_b32_e32 v154, 16, v199
	v_and_b32_e32 v155, 0xffff0000, v199
	v_lshlrev_b32_e32 v156, 16, v195
	v_and_b32_e32 v157, 0xffff0000, v195
	v_pk_fma_f32 v[126:127], v[126:127], v[214:215], v[216:217]
	v_pk_fma_f32 v[128:129], v[128:129], v[154:155], v[156:157]
	v_cvt_pk_bf16_f32 v156, v126, v127
	v_cvt_pk_bf16_f32 v157, v128, v129
	v_pk_mul_f32 v[126:127], v[126:127], v[126:127]
	v_pk_mul_f32 v[128:129], v[128:129], v[128:129]
	v_cvt_pk_bf16_f32 v154, v134, v135
	v_cvt_pk_bf16_f32 v155, v136, v137
	v_pk_fma_f32 v[126:127], v[134:135], v[134:135], v[126:127]
	v_pk_fma_f32 v[128:129], v[136:137], v[136:137], v[128:129]
	v_lshlrev_b32_e32 v134, 16, v204
	v_and_b32_e32 v135, 0xffff0000, v204
	v_lshlrev_b32_e32 v136, 16, v200
	v_and_b32_e32 v137, 0xffff0000, v200
	v_pk_fma_f32 v[118:119], v[118:119], v[134:135], v[136:137]
	v_lshlrev_b32_e32 v134, 16, v206
	v_and_b32_e32 v135, 0xffff0000, v206
	v_lshlrev_b32_e32 v136, 16, v202
	v_and_b32_e32 v137, 0xffff0000, v202
	v_pk_fma_f32 v[134:135], v[114:115], v[134:135], v[136:137]
	v_mul_f32_e32 v115, 0xbfb8aa3b, v116
	v_exp_f32_e32 v115, v115
	v_mul_f32_e32 v114, 0xbfb8aa3b, v120
	v_exp_f32_e32 v114, v114
	v_lshlrev_b32_e32 v120, 16, v205
	v_add_f32_e32 v115, 1.0, v115
	v_rcp_f32_e32 v116, v115
	v_mul_f32_e32 v115, 0xbfb8aa3b, v121
	v_exp_f32_e32 v115, v115
	v_add_f32_e32 v114, 1.0, v114
	v_rcp_f32_e32 v114, v114
	v_and_b32_e32 v121, 0xffff0000, v205
	v_add_f32_e32 v115, 1.0, v115
	v_rcp_f32_e32 v115, v115
	v_lshlrev_b32_e32 v136, 16, v201
	v_and_b32_e32 v137, 0xffff0000, v201
	v_lshl_add_u64 v[158:159], s[0:1], 0, v[186:187]
	v_pk_fma_f32 v[120:121], v[114:115], v[120:121], v[136:137]
	v_mul_f32_e32 v114, 0xbfb8aa3b, v117
	v_exp_f32_e32 v114, v114
	v_and_b32_e32 v115, 0xffff0000, v207
	v_lshlrev_b32_e32 v136, 16, v203
	v_and_b32_e32 v137, 0xffff0000, v203
	v_add_f32_e32 v114, 1.0, v114
	v_rcp_f32_e32 v117, v114
	v_lshlrev_b32_e32 v114, 16, v207
	v_lshl_add_u64 v[158:159], v[180:181], 1, v[158:159]
	global_store_dwordx4 v[158:159], v[154:157], off
	v_pk_fma_f32 v[136:137], v[116:117], v[114:115], v[136:137]
	v_cvt_pk_bf16_f32 v114, v118, v119
	v_cvt_pk_bf16_f32 v115, v120, v121
	v_cvt_pk_bf16_f32 v116, v134, v135
	v_cvt_pk_bf16_f32 v117, v136, v137
	global_store_dwordx4 v[158:159], v[114:117], off offset:256
	s_nop 1
	v_pk_mul_f32 v[114:115], v[134:135], v[134:135]
	v_pk_mul_f32 v[116:117], v[136:137], v[136:137]
	v_pk_fma_f32 v[114:115], v[118:119], v[118:119], v[114:115]
	v_add_f32_e32 v118, v126, v127
	v_add_f32_e32 v118, v128, v118
	v_add_f32_e32 v118, v129, v118
	v_add_f32_e32 v114, v114, v118
	v_pk_fma_f32 v[116:117], v[120:121], v[120:121], v[116:117]
	v_add_f32_e32 v114, v115, v114
	v_add_f32_e32 v114, v116, v114
	v_add_f32_e32 v114, v117, v114
	ds_bpermute_b32 v115, v211, v114
	s_waitcnt lgkmcnt(0)
	v_add_f32_e32 v114, v114, v115
	ds_bpermute_b32 v115, v212, v114
	s_and_saveexec_b64 s[4:5], vcc
	s_cbranch_execz .LBB0_804
	v_lshl_add_u64 v[116:117], v[182:183], 2, s[46:47]
	s_waitcnt lgkmcnt(0)
	v_add_f32_e32 v114, v114, v115
	global_atomic_add_f32 v[116:117], v114, off
; __device__ __forceinline__ float sigmoid_f(float x) { return __builtin_amdgcn_rcpf(1.0f + __builtin_amdgcn_exp2f(-1.4426950409f * x)); }
; __device__ __forceinline__ u32x4 pack8(f32x4 a, f32x4 b) { u32x4 w; w.x = cvt_pk_bf16(a[0], a[1]); w.y = cvt_pk_bf16(a[2], a[3]); w.z = cvt_pk_bf16(b[0], b[1]); w.w = cvt_pk_bf16(b[2], b[3]); return w; }
; __device__ __forceinline__ void unpack8(u32x4 g, f32x4& a, f32x4& b) { a = (f32x4){bf_lo(g.x), bf_hi(g.x), bf_lo(g.y), bf_hi(g.y)}; b = (f32x4){bf_lo(g.z), bf_hi(g.z), bf_lo(g.w), bf_hi(g.w)}; }
; #define GATE_LOAD(r, b) do { const int row_ = row0 + ((r) >> 2) * 128 + ((r) & 3) * 16; _Pragma("unroll") for (int bj = 0; bj < 2; ++bj) { const size_t off_ = (size_t)row_ * DM + col0 + bj * 128; \
;             hA[b][bj] = *(const u32x4*)(H1 + off_); pA[b][bj] = *(const u32x4*)(PLE + off_); } } while (0)
;     __device__ __forceinline__ void operator()(f32x4 (&acc)[2][2][4][2], const Unit& u, int wr, int wc, int fr, int fq) const {
;     ...
;         GATE_LOAD(0, 0);
; #pragma unroll
;         for (int r = 0; r < 8; ++r) {
;             const int ai = r >> 2, m = r & 3, b = r & 1;
;             if (r + 1 < 8) GATE_LOAD(r + 1, (r + 1) & 1);
;             const int row = row0 + ai * 128 + m * 16;
;             float ss = 0.f;
; #pragma unroll
;             for (int bj = 0; bj < 2; ++bj) {
;                 const size_t off = (size_t)row * DM + col0 + bj * 128;
;                 f32x4 p0, p1, o0, o1; unpack8(pA[b][bj], p0, p1); unpack8(hA[b][bj], o0, o1);
; #pragma unroll
;                 for (int j = 0; j < 4; ++j) { o0[j] += sigmoid_f(acc[ai][bj][m][0][j]) * p0[j]; o1[j] += sigmoid_f(acc[ai][bj][m][1][j]) * p1[j]; }
;                 *(u32x4*)(HB + off) = pack8(o0, o1);
; #pragma unroll
;                 for (int j = 0; j < 4; ++j) ss += o0[j] * o0[j] + o1[j] * o1[j];
;             }
;             ss += __shfl_xor(ss, 16); ss += __shfl_xor(ss, 32);
;             if (fq == 0) atomicAdd(ssq + row, ss);
;             asm volatile("" ::: "memory");
;         }
.LBB0_804:
	s_or_b64 exec, exec, s[4:5]
	v_add_u32_e32 v146, 32, v182
	v_ashrrev_i32_e32 v147, 31, v146
	s_waitcnt lgkmcnt(0)
	v_lshlrev_b64 v[114:115], 11, v[146:147]
	v_lshl_add_u64 v[114:115], v[114:115], 0, v[180:181]
	v_lshlrev_b64 v[114:115], 1, v[114:115]
	v_lshl_add_u64 v[116:117], s[66:67], 0, v[114:115]
	v_lshl_add_u64 v[118:119], s[44:45], 0, v[114:115]
	v_lshl_add_u64 v[118:119], v[118:119], 0, v[246:247]
	global_load_dwordx4 v[126:129], v[116:117], off
	s_nop 0
	global_load_dwordx4 v[114:117], v[116:117], off offset:256
	s_nop 0
	global_load_dwordx4 v[134:137], v[118:119], off
	s_nop 0
	global_load_dwordx4 v[118:121], v[118:119], off offset:1024
	v_mul_f32_e32 v110, 0xbfb8aa3b, v110
	v_mul_f32_e32 v111, 0xbfb8aa3b, v111
	v_exp_f32_e32 v110, v110
	v_mul_f32_e32 v106, 0xbfb8aa3b, v106
	v_exp_f32_e32 v111, v111
	v_mul_f32_e32 v107, 0xbfb8aa3b, v107
	v_exp_f32_e32 v106, v106
	v_exp_f32_e32 v107, v107
	v_add_f32_e32 v110, 1.0, v110
	v_add_f32_e32 v111, 1.0, v111
	v_rcp_f32_e32 v110, v110
	v_add_f32_e32 v106, 1.0, v106
	v_rcp_f32_e32 v111, v111
	v_add_f32_e32 v107, 1.0, v107
	v_rcp_f32_e32 v106, v106
	v_rcp_f32_e32 v107, v107
	v_mul_f32_e32 v112, 0xbfb8aa3b, v112
	s_waitcnt vmcnt(7)
	v_lshlrev_b32_e32 v150, 16, v142
	v_and_b32_e32 v151, 0xffff0000, v142
	v_lshlrev_b32_e32 v152, 16, v138
	v_and_b32_e32 v153, 0xffff0000, v138
	v_exp_f32_e32 v112, v112
	v_pk_fma_f32 v[110:111], v[110:111], v[150:151], v[152:153]
	v_lshlrev_b32_e32 v150, 16, v144
	v_and_b32_e32 v151, 0xffff0000, v144
	v_lshlrev_b32_e32 v152, 16, v140
	v_and_b32_e32 v153, 0xffff0000, v140
	v_pk_fma_f32 v[150:151], v[106:107], v[150:151], v[152:153]
	v_mul_f32_e32 v107, 0xbfb8aa3b, v108
	v_exp_f32_e32 v107, v107
	v_mul_f32_e32 v108, 0xbfb8aa3b, v113
	v_add_f32_e32 v106, 1.0, v112
	v_exp_f32_e32 v112, v108
	v_add_f32_e32 v107, 1.0, v107
	v_rcp_f32_e32 v108, v107
	v_mul_f32_e32 v109, 0xbfb8aa3b, v109
	v_add_f32_e32 v107, 1.0, v112
	v_rcp_f32_e32 v106, v106
	v_rcp_f32_e32 v107, v107
	v_exp_f32_e32 v109, v109
	v_mul_f32_e32 v102, 0xbfb8aa3b, v102
	v_mul_f32_e32 v103, 0xbfb8aa3b, v103
	v_lshlrev_b32_e32 v112, 16, v143
	v_and_b32_e32 v113, 0xffff0000, v143
	v_lshlrev_b32_e32 v138, 16, v139
	v_and_b32_e32 v139, 0xffff0000, v139
	v_exp_f32_e32 v102, v102
	v_mul_f32_e32 v98, 0xbfb8aa3b, v98
	v_exp_f32_e32 v103, v103
	v_mul_f32_e32 v99, 0xbfb8aa3b, v99
	v_pk_fma_f32 v[112:113], v[106:107], v[112:113], v[138:139]
	v_add_f32_e32 v106, 1.0, v109
	v_exp_f32_e32 v98, v98
	v_exp_f32_e32 v99, v99
	v_rcp_f32_e32 v109, v106
	v_add_f32_e32 v102, 1.0, v102
	v_add_f32_e32 v103, 1.0, v103
	v_lshlrev_b32_e32 v106, 16, v145
	v_and_b32_e32 v107, 0xffff0000, v145
	v_lshlrev_b32_e32 v138, 16, v141
	v_and_b32_e32 v139, 0xffff0000, v141
	v_rcp_f32_e32 v102, v102
	v_add_f32_e32 v98, 1.0, v98
	v_rcp_f32_e32 v103, v103
	v_add_f32_e32 v99, 1.0, v99
	v_pk_fma_f32 v[138:139], v[108:109], v[106:107], v[138:139]
	v_rcp_f32_e32 v98, v98
	v_rcp_f32_e32 v99, v99
	v_cvt_pk_bf16_f32 v109, v138, v139
	v_pk_mul_f32 v[140:141], v[150:151], v[150:151]
	v_pk_mul_f32 v[138:139], v[138:139], v[138:139]
	v_mul_f32_e32 v104, 0xbfb8aa3b, v104
	v_cvt_pk_bf16_f32 v106, v110, v111
	v_cvt_pk_bf16_f32 v107, v112, v113
	v_pk_fma_f32 v[110:111], v[110:111], v[110:111], v[140:141]
	v_pk_fma_f32 v[112:113], v[112:113], v[112:113], v[138:139]
	v_lshlrev_b32_e32 v138, 16, v130
	v_and_b32_e32 v139, 0xffff0000, v130
	v_lshlrev_b32_e32 v140, 16, v122
	v_and_b32_e32 v141, 0xffff0000, v122
	v_exp_f32_e32 v104, v104
	v_pk_fma_f32 v[102:103], v[102:103], v[138:139], v[140:141]
	v_lshlrev_b32_e32 v138, 16, v132
	v_and_b32_e32 v139, 0xffff0000, v132
	v_lshlrev_b32_e32 v140, 16, v124
	v_and_b32_e32 v141, 0xffff0000, v124
	v_pk_fma_f32 v[138:139], v[98:99], v[138:139], v[140:141]
	v_mul_f32_e32 v99, 0xbfb8aa3b, v100
	v_exp_f32_e32 v99, v99
	v_mul_f32_e32 v100, 0xbfb8aa3b, v105
	v_add_f32_e32 v98, 1.0, v104
	v_exp_f32_e32 v104, v100
	v_add_f32_e32 v99, 1.0, v99
	v_rcp_f32_e32 v100, v99
	v_mul_f32_e32 v101, 0xbfb8aa3b, v101
	v_add_f32_e32 v99, 1.0, v104
	v_rcp_f32_e32 v98, v98
	v_rcp_f32_e32 v99, v99
	v_exp_f32_e32 v101, v101
	v_lshlrev_b32_e32 v104, 16, v131
	v_and_b32_e32 v105, 0xffff0000, v131
	v_lshlrev_b32_e32 v122, 16, v123
	v_and_b32_e32 v123, 0xffff0000, v123
	v_pk_fma_f32 v[104:105], v[98:99], v[104:105], v[122:123]
	v_add_f32_e32 v98, 1.0, v101
	v_rcp_f32_e32 v101, v98
	v_lshlrev_b32_e32 v98, 16, v133
	v_and_b32_e32 v99, 0xffff0000, v133
	v_lshlrev_b32_e32 v122, 16, v125
	v_and_b32_e32 v123, 0xffff0000, v125
	v_add_f32_e32 v110, v110, v111
	v_pk_fma_f32 v[122:123], v[100:101], v[98:99], v[122:123]
	v_pk_mul_f32 v[98:99], v[138:139], v[138:139]
	v_add_f32_e32 v110, v112, v110
	v_pk_fma_f32 v[98:99], v[102:103], v[102:103], v[98:99]
	v_add_f32_e32 v110, v113, v110
	v_pk_mul_f32 v[100:101], v[122:123], v[122:123]
	v_add_f32_e32 v98, v98, v110
	v_pk_fma_f32 v[100:101], v[104:105], v[104:105], v[100:101]
	v_add_f32_e32 v98, v99, v98
	v_add_f32_e32 v98, v100, v98
	v_add_f32_e32 v101, v101, v98
	ds_bpermute_b32 v112, v211, v101
	v_lshlrev_b64 v[148:149], 12, v[184:185]
	v_lshl_add_u64 v[98:99], s[0:1], 0, v[148:149]
	v_lshl_add_u64 v[110:111], v[180:181], 1, v[98:99]
	v_cvt_pk_bf16_f32 v108, v150, v151
	s_waitcnt lgkmcnt(0)
	v_add_f32_e32 v98, v101, v112
	ds_bpermute_b32 v99, v212, v98
	v_cvt_pk_bf16_f32 v100, v102, v103
	v_cvt_pk_bf16_f32 v101, v104, v105
	v_cvt_pk_bf16_f32 v102, v138, v139
	v_cvt_pk_bf16_f32 v103, v122, v123
	global_store_dwordx4 v[110:111], v[106:109], off
	global_store_dwordx4 v[110:111], v[100:103], off offset:256
	s_and_saveexec_b64 s[4:5], vcc
	s_cbranch_execz .LBB0_806
	v_lshl_add_u64 v[100:101], v[184:185], 2, s[46:47]
	s_waitcnt lgkmcnt(0)
	v_add_f32_e32 v98, v98, v99
	global_atomic_add_f32 v[100:101], v98, off

; #define PG8_WAIT_V(n) asm volatile("s_waitcnt vmcnt(" #n ")" ::: "memory")
; #define PG8_BAR __builtin_amdgcn_s_barrier()
; template <class Epi, class Order = StaticOrder, bool HALFN = false>
; __device__ __forceinline__ void gemm_phase(LAS unsigned char* lds, const Gemm g, const Epi& E) {
;     ...
;     PG8_WAIT_V(0);
;     PG8_BAR;
.LBB0_821:
	v_mov_b32_e32 v192, 0x4800
	v_mov_b32_e32 v193, 0x1800
	v_mov_b32_e32 v194, 0x3e000000
	v_mov_b32_e32 v195, 0x3eaaaaab
	v_mov_b32_e32 v196, 0x3e800000
	v_mov_b32_e32 v197, 0x3e4ccccd
	v_mov_b32_e32 v198, 0x3e2aaaab
	v_mov_b32_e32 v199, 0x3e124925
	v_mov_b32_e32 v200, 0x3d800000
	v_mov_b32_e32 v201, 0x3de38e39
	v_mov_b32_e32 v202, 0x3dcccccd
	v_mov_b32_e32 v203, 0x3dba2e8c
	v_mov_b32_e32 v204, 0x3daaaaab
	v_mov_b32_e32 v205, 0x3d9d89d9
	v_mov_b32_e32 v206, 0x3d924925
	v_mov_b32_e32 v207, 0x3d888889
	s_waitcnt vmcnt(0)
	s_barrier
